# same but only in the P4 GEMM loop
# baseline (speedup 1.0000x reference)
.LBB0_656:
	v_add_u32_e32 v1, s69, v177
	ds_read_b128 v[132:135], v1
	ds_read_b128 v[136:139], v1 offset:1024
	ds_read_b128 v[140:143], v1 offset:2048
	ds_read_b128 v[144:147], v1 offset:3072
	v_add_u32_e32 v1, s70, v177
	s_add_u32 s28, s26, s38
	ds_read_b128 v[180:183], v1
	ds_read_b128 v[184:187], v1 offset:1024
	ds_read_b128 v[188:191], v1 offset:2048
	ds_read_b128 v[192:195], v1 offset:3072
	s_addc_u32 s29, s27, s39
	s_add_u32 s28, s28, 0x100
	s_addc_u32 s29, s29, 0
	s_add_u32 s30, s73, s38
	s_addc_u32 s31, s74, s39
	s_cmpk_eq_i32 s38, 0xf00
	s_cselect_b32 s43, s19, s29
	s_cselect_b32 s42, s71, s28
	s_cselect_b32 s41, s17, s31
	s_cselect_b32 s40, s72, s30
	v_lshl_add_u64 v[234:235], v[170:171], 0, s[38:39]
	s_add_i32 s76, s50, 0xc000
	ds_read_b128 v[196:199], v179
	ds_read_b128 v[200:203], v179 offset:1024
	ds_read_b128 v[204:207], v179 offset:2048
	ds_read_b128 v[208:211], v179 offset:3072
	ds_read_b128 v[212:215], v179 offset:4096
	ds_read_b128 v[216:219], v179 offset:5120
	ds_read_b128 v[220:223], v179 offset:6144
	ds_read_b128 v[224:227], v179 offset:7168
	v_lshl_add_u64 v[2:3], v[172:173], 0, s[38:39]
	s_add_i32 s77, s50, 0xe000
	s_waitcnt vmcnt(6)
	s_waitcnt lgkmcnt(0)
	s_barrier
	s_setprio 1
	s_waitcnt lgkmcnt(0)
	v_mfma_f32_16x16x32_bf16 v[128:131], v[132:135], v[196:199], v[128:131]
	v_mfma_f32_16x16x32_bf16 v[124:127], v[140:143], v[196:199], v[124:127]
	s_mov_b32 m0, s76
	v_mfma_f32_16x16x32_bf16 v[112:115], v[132:135], v[204:207], v[112:115]
	global_load_lds_dwordx4 v[234:235], off
	v_mfma_f32_16x16x32_bf16 v[108:111], v[140:143], v[204:207], v[108:111]
	v_mfma_f32_16x16x32_bf16 v[96:99], v[132:135], v[212:215], v[96:99]
	v_mfma_f32_16x16x32_bf16 v[92:95], v[140:143], v[212:215], v[92:95]
	s_mov_b32 m0, s77
	v_mfma_f32_16x16x32_bf16 v[80:83], v[132:135], v[220:223], v[80:83]
	global_load_lds_dwordx4 v[2:3], off
	v_mfma_f32_16x16x32_bf16 v[76:79], v[140:143], v[220:223], v[76:79]
	v_mfma_f32_16x16x32_bf16 v[128:131], v[136:139], v[200:203], v[128:131]
	v_mfma_f32_16x16x32_bf16 v[124:127], v[144:147], v[200:203], v[124:127]
	v_mfma_f32_16x16x32_bf16 v[112:115], v[136:139], v[208:211], v[112:115]
	v_mfma_f32_16x16x32_bf16 v[108:111], v[144:147], v[208:211], v[108:111]
	v_mfma_f32_16x16x32_bf16 v[96:99], v[136:139], v[216:219], v[96:99]
	v_mfma_f32_16x16x32_bf16 v[92:95], v[144:147], v[216:219], v[92:95]
	v_mfma_f32_16x16x32_bf16 v[80:83], v[136:139], v[224:227], v[80:83]
	v_mfma_f32_16x16x32_bf16 v[76:79], v[144:147], v[224:227], v[76:79]
	s_setprio 0
	s_setprio 1
	v_mfma_f32_16x16x32_bf16 v[120:123], v[180:183], v[196:199], v[120:123]
	v_mfma_f32_16x16x32_bf16 v[116:119], v[188:191], v[196:199], v[116:119]
	v_mfma_f32_16x16x32_bf16 v[104:107], v[180:183], v[204:207], v[104:107]
	v_mfma_f32_16x16x32_bf16 v[100:103], v[188:191], v[204:207], v[100:103]
	v_mfma_f32_16x16x32_bf16 v[88:91], v[180:183], v[212:215], v[88:91]
	v_mfma_f32_16x16x32_bf16 v[84:87], v[188:191], v[212:215], v[84:87]
	v_mfma_f32_16x16x32_bf16 v[72:75], v[180:183], v[220:223], v[72:75]
	v_mfma_f32_16x16x32_bf16 v[68:71], v[188:191], v[220:223], v[68:71]
	v_mfma_f32_16x16x32_bf16 v[120:123], v[184:187], v[200:203], v[120:123]
	v_mfma_f32_16x16x32_bf16 v[116:119], v[192:195], v[200:203], v[116:119]
	v_mfma_f32_16x16x32_bf16 v[104:107], v[184:187], v[208:211], v[104:107]
	v_mfma_f32_16x16x32_bf16 v[100:103], v[192:195], v[208:211], v[100:103]
	v_mfma_f32_16x16x32_bf16 v[88:91], v[184:187], v[216:219], v[88:91]
	v_mfma_f32_16x16x32_bf16 v[84:87], v[192:195], v[216:219], v[84:87]
	v_mfma_f32_16x16x32_bf16 v[72:75], v[184:187], v[224:227], v[72:75]
	v_mfma_f32_16x16x32_bf16 v[68:71], v[192:195], v[224:227], v[68:71]
	s_setprio 0
	s_barrier
	s_add_i32 s28, s69, s49
	v_lshl_add_u64 v[174:175], s[40:41], 0, v[150:151]
	s_mov_b32 s76, s28
	ds_read_b128 v[196:199], v179 offset:16384
	ds_read_b128 v[200:203], v179 offset:17408
	ds_read_b128 v[204:207], v179 offset:18432
	ds_read_b128 v[208:211], v179 offset:19456
	ds_read_b128 v[212:215], v179 offset:20480
	ds_read_b128 v[216:219], v179 offset:21504
	ds_read_b128 v[220:223], v179 offset:22528
	ds_read_b128 v[224:227], v179 offset:23552
	s_add_i32 s77, s28, 0x2000
	s_add_u32 s28, s40, 0x80000
	v_lshl_add_u64 v[228:229], s[40:41], 0, v[154:155]
	s_addc_u32 s29, s41, 0
	s_add_i32 s30, s70, s49
	v_lshl_add_u64 v[234:235], s[28:29], 0, v[150:151]
	s_mov_b32 s78, s30
	v_lshl_add_u64 v[230:231], s[42:43], 0, v[148:149]
	v_lshl_add_u64 v[236:237], s[28:29], 0, v[154:155]
	s_add_i32 s79, s30, 0x2000
	v_lshl_add_u64 v[232:233], s[42:43], 0, v[152:153]
	s_mov_b32 s80, s50
	s_mov_b32 s81, s51
	s_waitcnt vmcnt(2)
	s_waitcnt lgkmcnt(0)
	s_barrier
	s_setprio 1
	s_waitcnt lgkmcnt(0)
	v_mfma_f32_16x16x32_bf16 v[64:67], v[132:135], v[196:199], v[64:67]
	v_mfma_f32_16x16x32_bf16 v[60:63], v[140:143], v[196:199], v[60:63]
	s_mov_b32 m0, s76
	v_mfma_f32_16x16x32_bf16 v[48:51], v[132:135], v[204:207], v[48:51]
	global_load_lds_dwordx4 v[174:175], off
	v_mfma_f32_16x16x32_bf16 v[44:47], v[140:143], v[204:207], v[44:47]
	v_mfma_f32_16x16x32_bf16 v[32:35], v[132:135], v[212:215], v[32:35]
	v_mfma_f32_16x16x32_bf16 v[28:31], v[140:143], v[212:215], v[28:31]
	s_mov_b32 m0, s77
	v_mfma_f32_16x16x32_bf16 v[16:19], v[132:135], v[220:223], v[16:19]
	global_load_lds_dwordx4 v[228:229], off
	v_mfma_f32_16x16x32_bf16 v[12:15], v[140:143], v[220:223], v[12:15]
	v_mfma_f32_16x16x32_bf16 v[64:67], v[136:139], v[200:203], v[64:67]
	v_mfma_f32_16x16x32_bf16 v[60:63], v[144:147], v[200:203], v[60:63]
	s_mov_b32 m0, s78
	v_mfma_f32_16x16x32_bf16 v[48:51], v[136:139], v[208:211], v[48:51]
	global_load_lds_dwordx4 v[234:235], off
	v_mfma_f32_16x16x32_bf16 v[44:47], v[144:147], v[208:211], v[44:47]
	v_mfma_f32_16x16x32_bf16 v[32:35], v[136:139], v[216:219], v[32:35]
	v_mfma_f32_16x16x32_bf16 v[28:31], v[144:147], v[216:219], v[28:31]
	s_mov_b32 m0, s79
	v_mfma_f32_16x16x32_bf16 v[16:19], v[136:139], v[224:227], v[16:19]
	global_load_lds_dwordx4 v[236:237], off
	v_mfma_f32_16x16x32_bf16 v[12:15], v[144:147], v[224:227], v[12:15]
	s_setprio 0
	s_setprio 1
	v_mfma_f32_16x16x32_bf16 v[56:59], v[180:183], v[196:199], v[56:59]
	v_mfma_f32_16x16x32_bf16 v[52:55], v[188:191], v[196:199], v[52:55]
	s_mov_b32 m0, s80
	v_mfma_f32_16x16x32_bf16 v[40:43], v[180:183], v[204:207], v[40:43]
	global_load_lds_dwordx4 v[230:231], off
	v_mfma_f32_16x16x32_bf16 v[36:39], v[188:191], v[204:207], v[36:39]
	v_mfma_f32_16x16x32_bf16 v[24:27], v[180:183], v[212:215], v[24:27]
	v_mfma_f32_16x16x32_bf16 v[20:23], v[188:191], v[212:215], v[20:23]
	s_mov_b32 m0, s81
	v_mfma_f32_16x16x32_bf16 v[8:11], v[180:183], v[220:223], v[8:11]
	global_load_lds_dwordx4 v[232:233], off
	v_mfma_f32_16x16x32_bf16 v[2:5], v[188:191], v[220:223], v[4:7]
	v_mfma_f32_16x16x32_bf16 v[56:59], v[184:187], v[200:203], v[56:59]
	v_mfma_f32_16x16x32_bf16 v[52:55], v[192:195], v[200:203], v[52:55]
	v_mfma_f32_16x16x32_bf16 v[40:43], v[184:187], v[208:211], v[40:43]
	v_mfma_f32_16x16x32_bf16 v[36:39], v[192:195], v[208:211], v[36:39]
	v_mfma_f32_16x16x32_bf16 v[24:27], v[184:187], v[216:219], v[24:27]
	v_mfma_f32_16x16x32_bf16 v[20:23], v[192:195], v[216:219], v[20:23]
	v_mfma_f32_16x16x32_bf16 v[8:11], v[184:187], v[224:227], v[8:11]
	v_mfma_f32_16x16x32_bf16 v[2:5], v[192:195], v[224:227], v[2:5]
	s_setprio 0
	s_barrier
	s_add_i32 s30, 0, 0x18000
	v_add_u32_e32 v1, s30, v177
	s_add_i32 s31, 0, 0x1c000
	ds_read_b128 v[132:135], v1
	ds_read_b128 v[136:139], v1 offset:1024
	ds_read_b128 v[140:143], v1 offset:2048
	ds_read_b128 v[144:147], v1 offset:3072
	v_add_u32_e32 v1, s31, v177
	ds_read_b128 v[180:183], v1
	ds_read_b128 v[184:187], v1 offset:1024
	ds_read_b128 v[188:191], v1 offset:2048
	ds_read_b128 v[192:195], v1 offset:3072
	s_add_u32 s28, s42, 0x80000
	s_addc_u32 s29, s43, 0
	s_mov_b32 s76, s62
	v_lshl_add_u64 v[234:235], s[28:29], 0, v[148:149]
	ds_read_b128 v[196:199], v179 offset:32768
	ds_read_b128 v[200:203], v179 offset:33792
	ds_read_b128 v[204:207], v179 offset:34816
	ds_read_b128 v[208:211], v179 offset:35840
	ds_read_b128 v[212:215], v179 offset:36864
	ds_read_b128 v[216:219], v179 offset:37888
	ds_read_b128 v[220:223], v179 offset:38912
	ds_read_b128 v[224:227], v179 offset:39936
	v_lshl_add_u64 v[6:7], s[28:29], 0, v[152:153]
	s_mov_b32 s77, s63
	s_waitcnt vmcnt(6)
	s_waitcnt lgkmcnt(0)
	s_barrier
	s_setprio 1
	s_waitcnt lgkmcnt(0)
	v_mfma_f32_16x16x32_bf16 v[128:131], v[132:135], v[196:199], v[128:131]
	v_mfma_f32_16x16x32_bf16 v[124:127], v[140:143], v[196:199], v[124:127]
	s_mov_b32 m0, s76
	v_mfma_f32_16x16x32_bf16 v[112:115], v[132:135], v[204:207], v[112:115]
	global_load_lds_dwordx4 v[234:235], off
	v_mfma_f32_16x16x32_bf16 v[108:111], v[140:143], v[204:207], v[108:111]
	v_mfma_f32_16x16x32_bf16 v[96:99], v[132:135], v[212:215], v[96:99]
	v_mfma_f32_16x16x32_bf16 v[92:95], v[140:143], v[212:215], v[92:95]
	s_mov_b32 m0, s77
	v_mfma_f32_16x16x32_bf16 v[80:83], v[132:135], v[220:223], v[80:83]
	global_load_lds_dwordx4 v[6:7], off
	v_mfma_f32_16x16x32_bf16 v[76:79], v[140:143], v[220:223], v[76:79]
	v_mfma_f32_16x16x32_bf16 v[128:131], v[136:139], v[200:203], v[128:131]
	v_mfma_f32_16x16x32_bf16 v[124:127], v[144:147], v[200:203], v[124:127]
	v_mfma_f32_16x16x32_bf16 v[112:115], v[136:139], v[208:211], v[112:115]
	v_mfma_f32_16x16x32_bf16 v[108:111], v[144:147], v[208:211], v[108:111]
	v_mfma_f32_16x16x32_bf16 v[96:99], v[136:139], v[216:219], v[96:99]
	v_mfma_f32_16x16x32_bf16 v[92:95], v[144:147], v[216:219], v[92:95]
	v_mfma_f32_16x16x32_bf16 v[80:83], v[136:139], v[224:227], v[80:83]
	v_mfma_f32_16x16x32_bf16 v[76:79], v[144:147], v[224:227], v[76:79]
	s_setprio 0
	s_setprio 1
	v_mfma_f32_16x16x32_bf16 v[120:123], v[180:183], v[196:199], v[120:123]
	v_mfma_f32_16x16x32_bf16 v[116:119], v[188:191], v[196:199], v[116:119]
	v_mfma_f32_16x16x32_bf16 v[104:107], v[180:183], v[204:207], v[104:107]
	v_mfma_f32_16x16x32_bf16 v[100:103], v[188:191], v[204:207], v[100:103]
	v_mfma_f32_16x16x32_bf16 v[88:91], v[180:183], v[212:215], v[88:91]
	v_mfma_f32_16x16x32_bf16 v[84:87], v[188:191], v[212:215], v[84:87]
	v_mfma_f32_16x16x32_bf16 v[72:75], v[180:183], v[220:223], v[72:75]
	v_mfma_f32_16x16x32_bf16 v[68:71], v[188:191], v[220:223], v[68:71]
	v_mfma_f32_16x16x32_bf16 v[120:123], v[184:187], v[200:203], v[120:123]
	v_mfma_f32_16x16x32_bf16 v[116:119], v[192:195], v[200:203], v[116:119]
	v_mfma_f32_16x16x32_bf16 v[104:107], v[184:187], v[208:211], v[104:107]
	v_mfma_f32_16x16x32_bf16 v[100:103], v[192:195], v[208:211], v[100:103]
	v_mfma_f32_16x16x32_bf16 v[88:91], v[184:187], v[216:219], v[88:91]
	v_mfma_f32_16x16x32_bf16 v[84:87], v[192:195], v[216:219], v[84:87]
	v_mfma_f32_16x16x32_bf16 v[72:75], v[184:187], v[224:227], v[72:75]
	v_mfma_f32_16x16x32_bf16 v[68:71], v[192:195], v[224:227], v[68:71]
	s_setprio 0
	s_barrier
	s_add_i32 s28, s30, s49
	v_lshl_add_u64 v[234:235], v[174:175], 0, s[12:13]
	s_mov_b32 s76, s28
	ds_read_b128 v[196:199], v179 offset:49152
	ds_read_b128 v[200:203], v179 offset:50176
	ds_read_b128 v[204:207], v179 offset:51200
	ds_read_b128 v[208:211], v179 offset:52224
	ds_read_b128 v[212:215], v179 offset:53248
	ds_read_b128 v[216:219], v179 offset:54272
	ds_read_b128 v[220:223], v179 offset:55296
	ds_read_b128 v[224:227], v179 offset:56320
	s_add_i32 s77, s28, 0x2000
	s_add_u32 s28, s40, 0x80080
	v_lshl_add_u64 v[236:237], v[228:229], 0, s[12:13]
	s_addc_u32 s29, s41, 0
	s_add_i32 s30, s31, s49
	v_lshl_add_u64 v[238:239], s[28:29], 0, v[150:151]
	s_mov_b32 s78, s30
	v_lshl_add_u64 v[240:241], s[28:29], 0, v[154:155]
	s_add_i32 s79, s30, 0x2000
	v_lshl_add_u64 v[244:245], v[230:231], 0, s[12:13]
	s_mov_b32 s80, s65
	v_lshl_add_u64 v[246:247], v[232:233], 0, s[12:13]
	s_mov_b32 s81, s66
	s_waitcnt vmcnt(2)
	s_waitcnt lgkmcnt(0)
	s_barrier
	s_setprio 1
	s_waitcnt lgkmcnt(0)
	v_mfma_f32_16x16x32_bf16 v[64:67], v[132:135], v[196:199], v[64:67]
	v_mfma_f32_16x16x32_bf16 v[60:63], v[140:143], v[196:199], v[60:63]
	s_mov_b32 m0, s76
	v_mfma_f32_16x16x32_bf16 v[48:51], v[132:135], v[204:207], v[48:51]
	global_load_lds_dwordx4 v[234:235], off
	v_mfma_f32_16x16x32_bf16 v[44:47], v[140:143], v[204:207], v[44:47]
	v_mfma_f32_16x16x32_bf16 v[32:35], v[132:135], v[212:215], v[32:35]
	v_mfma_f32_16x16x32_bf16 v[28:31], v[140:143], v[212:215], v[28:31]
	s_mov_b32 m0, s77
	v_mfma_f32_16x16x32_bf16 v[16:19], v[132:135], v[220:223], v[16:19]
	global_load_lds_dwordx4 v[236:237], off
	v_mfma_f32_16x16x32_bf16 v[12:15], v[140:143], v[220:223], v[12:15]
	v_mfma_f32_16x16x32_bf16 v[64:67], v[136:139], v[200:203], v[64:67]
	v_mfma_f32_16x16x32_bf16 v[60:63], v[144:147], v[200:203], v[60:63]
	s_mov_b32 m0, s78
	v_mfma_f32_16x16x32_bf16 v[48:51], v[136:139], v[208:211], v[48:51]
	global_load_lds_dwordx4 v[238:239], off
	v_mfma_f32_16x16x32_bf16 v[44:47], v[144:147], v[208:211], v[44:47]
	v_mfma_f32_16x16x32_bf16 v[32:35], v[136:139], v[216:219], v[32:35]
	v_mfma_f32_16x16x32_bf16 v[28:31], v[144:147], v[216:219], v[28:31]
	s_mov_b32 m0, s79
	v_mfma_f32_16x16x32_bf16 v[16:19], v[136:139], v[224:227], v[16:19]
	global_load_lds_dwordx4 v[240:241], off
	v_mfma_f32_16x16x32_bf16 v[12:15], v[144:147], v[224:227], v[12:15]
	s_setprio 0
	s_setprio 1
	v_mfma_f32_16x16x32_bf16 v[56:59], v[180:183], v[196:199], v[56:59]
	v_mfma_f32_16x16x32_bf16 v[52:55], v[188:191], v[196:199], v[52:55]
	s_mov_b32 m0, s80
	v_mfma_f32_16x16x32_bf16 v[40:43], v[180:183], v[204:207], v[40:43]
	global_load_lds_dwordx4 v[244:245], off
	v_mfma_f32_16x16x32_bf16 v[36:39], v[188:191], v[204:207], v[36:39]
	v_mfma_f32_16x16x32_bf16 v[24:27], v[180:183], v[212:215], v[24:27]
	v_mfma_f32_16x16x32_bf16 v[20:23], v[188:191], v[212:215], v[20:23]
	s_mov_b32 m0, s81
	v_mfma_f32_16x16x32_bf16 v[6:9], v[180:183], v[220:223], v[8:11]
	global_load_lds_dwordx4 v[246:247], off
	v_mfma_f32_16x16x32_bf16 v[2:5], v[188:191], v[220:223], v[2:5]
	v_mfma_f32_16x16x32_bf16 v[56:59], v[184:187], v[200:203], v[56:59]
	v_mfma_f32_16x16x32_bf16 v[52:55], v[192:195], v[200:203], v[52:55]
	v_mfma_f32_16x16x32_bf16 v[40:43], v[184:187], v[208:211], v[40:43]
	v_mfma_f32_16x16x32_bf16 v[36:39], v[192:195], v[208:211], v[36:39]
	v_mfma_f32_16x16x32_bf16 v[24:27], v[184:187], v[216:219], v[24:27]
	v_mfma_f32_16x16x32_bf16 v[20:23], v[192:195], v[216:219], v[20:23]
	v_mfma_f32_16x16x32_bf16 v[8:11], v[184:187], v[224:227], v[6:9]
	v_mfma_f32_16x16x32_bf16 v[4:7], v[192:195], v[224:227], v[2:5]
	s_setprio 0
	s_barrier
	s_add_i32 s75, s75, 2
	s_add_u32 s38, s38, 0x100
	s_addc_u32 s39, s39, 0
	s_cmp_gt_u32 s75, 29
	s_cbranch_scc1 .LBB0_659

	.amdhsa_kernel _Z14fwd_megakernel4Args
		.amdhsa_group_segment_fixed_size 0
		.amdhsa_private_segment_fixed_size 0
		.amdhsa_kernarg_size 384
		.amdhsa_user_sgpr_count 2
		.amdhsa_user_sgpr_dispatch_ptr 0
		.amdhsa_user_sgpr_queue_ptr 0
		.amdhsa_user_sgpr_kernarg_segment_ptr 1
		.amdhsa_user_sgpr_dispatch_id 0
		.amdhsa_user_sgpr_kernarg_preload_length 0
		.amdhsa_user_sgpr_kernarg_preload_offset 0
		.amdhsa_user_sgpr_private_segment_size 0
		.amdhsa_uses_dynamic_stack 0
		.amdhsa_enable_private_segment 0
		.amdhsa_system_sgpr_workgroup_id_x 1
		.amdhsa_system_sgpr_workgroup_id_y 0
		.amdhsa_system_sgpr_workgroup_id_z 0
		.amdhsa_system_sgpr_workgroup_info 0
		.amdhsa_system_vgpr_workitem_id 2
		.amdhsa_next_free_vgpr 256
		.amdhsa_next_free_sgpr 98
		.amdhsa_accum_offset 256
		.amdhsa_reserve_vcc 1
		.amdhsa_float_round_mode_32 0
		.amdhsa_float_round_mode_16_64 0
		.amdhsa_float_denorm_mode_32 3
		.amdhsa_float_denorm_mode_16_64 3
		.amdhsa_dx10_clamp 1
		.amdhsa_ieee_mode 1
		.amdhsa_fp16_overflow 0
		.amdhsa_tg_split 0
		.amdhsa_exception_fp_ieee_invalid_op 0
		.amdhsa_exception_fp_denorm_src 0
		.amdhsa_exception_fp_ieee_div_zero 0
		.amdhsa_exception_fp_ieee_overflow 0
		.amdhsa_exception_fp_ieee_underflow 0
		.amdhsa_exception_fp_ieee_inexact 0
		.amdhsa_exception_int_div_zero 0
	.end_amdhsa_kernel

amdhsa.kernels:
  - .agpr_count:     0
    .args:
      - .offset:         0
        .size:           128
        .value_kind:     by_value
      - .offset:         128
        .size:           4
        .value_kind:     hidden_block_count_x
      - .offset:         132
        .size:           4
        .value_kind:     hidden_block_count_y
      - .offset:         136
        .size:           4
        .value_kind:     hidden_block_count_z
      - .offset:         140
        .size:           2
        .value_kind:     hidden_group_size_x
      - .offset:         142
        .size:           2
        .value_kind:     hidden_group_size_y
      - .offset:         144
        .size:           2
        .value_kind:     hidden_group_size_z
      - .offset:         146
        .size:           2
        .value_kind:     hidden_remainder_x
      - .offset:         148
        .size:           2
        .value_kind:     hidden_remainder_y
      - .offset:         150
        .size:           2
        .value_kind:     hidden_remainder_z
      - .offset:         168
        .size:           8
        .value_kind:     hidden_global_offset_x
      - .offset:         176
        .size:           8
        .value_kind:     hidden_global_offset_y
      - .offset:         184
        .size:           8
        .value_kind:     hidden_global_offset_z
      - .offset:         192
        .size:           2
        .value_kind:     hidden_grid_dims
      - .offset:         216
        .size:           8
        .value_kind:     hidden_multigrid_sync_arg
      - .offset:         248
        .size:           4
        .value_kind:     hidden_dynamic_lds_size
    .group_segment_fixed_size: 0
    .kernarg_segment_align: 8
    .kernarg_segment_size: 384
    .language:       OpenCL C
    .language_version:
      - 2
      - 0
    .max_flat_workgroup_size: 512
    .name:           _Z14fwd_megakernel4Args
    .private_segment_fixed_size: 0
    .sgpr_count:     104
    .sgpr_spill_count: 9
    .symbol:         _Z14fwd_megakernel4Args.kd
    .uniform_work_group_size: 1
    .uses_dynamic_stack: false
    .vgpr_count:     256
    .vgpr_spill_count: 0
    .wavefront_size: 64
